# baseline (speedup 1.0000x reference)
; template <bool MLA>
; __device__ __forceinline__ float attn_scores(f32x16& sa, float c1, float slope2, int qpos, int q0w, int kpos0, int h5, bool maskit) {
;     ...
; #pragma unroll
;         for (int r = 0; r < 16; ++r) {
;             float v = sa[r] * c1;
;             if (maskit && (kpos0 + 8 * (r >> 2) + (r & 3) + 4 * h5 >= L)) v = -INFINITY;
;             sa[r] = v;
;             mx = fmaxf(mx, v);
;         }
;     } else {
;         const float dq = (float)(qpos - kpos0 - 4 * h5);
;         const int rel = q0w - kpos0;
;         if (rel > 31 || rel < -31) {
;             const float sgn = rel > 0 ? 1.0f : -1.0f;
;             const float A = -sgn * slope2 * dq;
;             const float ss = sgn * slope2;
; #pragma unroll
;             for (int r = 0; r < 16; ++r) {
; template <bool MLA>
; __device__ __forceinline__ void attn_item(unsigned char* smem, const Params& p, int b, int hh, int qt) {
;     ...
;     for (int kt = 0; kt < NKT; ++kt) {
;         const int k0 = kt * 64;
;         const unsigned char* Kc = S0 + stage * STGB;
;         const unsigned char* Vc = Kc + KBYTES;
;         if (kt + 2 < NKT) { const int st2 = stage >= 1 ? stage - 1 : 2; ATTN_DMA(st2); }
;         bf16x8 ka[4], kb[4], kc[4], vf[8];
; #pragma unroll
;         for (int i = 0; i < 4; ++i) ka[i] = KRD(0, i);
;         SB_();
; #pragma unroll
;         for (int hf = 0; hf < 2; ++hf) {
;             if (hf == 1 && kt == NKT - 1) break;
;             f32x16 sa;
; #pragma unroll
;             for (int r = 0; r < 16; ++r) sa[r] = 0.f;
;             if constexpr (MLA) {
;                 __builtin_amdgcn_s_setprio(1);
; #pragma unroll
;                 for (int i = 0; i < 4; ++i) {
;                     sa = __builtin_amdgcn_mfma_f32_32x32x16_bf16(ka[i], qf[i], sa, 0, 0, 0);
;                     kb[i] = KRD(hf, 4 + i);
;                 }
;                 SB_();
; #pragma unroll
;                 for (int i = 0; i < 4; ++i) {
;                     sa = __builtin_amdgcn_mfma_f32_32x32x16_bf16(kb[i], qf[4 + i], sa, 0, 0, 0);
;                     kc[i] = KRD(hf, 8 + i);
;                 }
;                 SB_();
; #pragma unroll
;                 for (int d = 0; d < 2; ++d) { vf[2 * d] = VRD(hf, d, 0); vf[2 * d + 1] = VRD(hf, d, 1); }
; #pragma unroll
;                 for (int i = 0; i < 4; ++i) sa = __builtin_amdgcn_mfma_f32_32x32x16_bf16(kc[i], qf[8 + i], sa, 0, 0, 0);
.LBB0_867:
	s_mul_i32 s3, s2, 0xa000
	s_add_i32 s6, s3, 0xffff6000
	s_cmp_gt_i32 s2, 0
	s_cselect_b32 s6, s6, 0x14000
	v_add_u32_e32 v230, s6, v199
	v_add_u32_e32 v70, s3, v200
	v_readfirstlane_b32 s6, v230
	v_add_u32_e32 v203, v70, v192
	v_add_u32_e32 v205, v70, v196
	v_add_u32_e32 v204, v70, v193
	ds_read_b128 v[66:69], v203
	ds_read_b128 v[130:133], v204
	v_add_u32_e32 v206, v70, v197
	ds_read_b128 v[134:137], v205
	ds_read_b128 v[138:141], v206
	v_or_b32_e32 v202, s3, v194
	s_setprio 1
	s_waitcnt lgkmcnt(0)
	v_mfma_f32_32x32x16_bf16 v[66:81], v[66:69], v[110:113], 0
	ds_read_b128 v[142:145], v203 offset:128
	v_mfma_f32_32x32x16_bf16 v[66:81], v[130:133], v[106:109], v[66:81]
	ds_read_b128 v[130:133], v204 offset:128
	v_mfma_f32_32x32x16_bf16 v[66:81], v[134:137], v[102:105], v[66:81]
	ds_read_b128 v[134:137], v205 offset:128
	v_mfma_f32_32x32x16_bf16 v[66:81], v[138:141], v[98:101], v[66:81]
	ds_read_b128 v[138:141], v206 offset:128
	ds_read_b128 v[208:211], v203 offset:256
	ds_read_b128 v[212:215], v204 offset:256
	ds_read_b128 v[222:225], v205 offset:256
	ds_read_b128 v[226:229], v206 offset:256
	s_waitcnt lgkmcnt(0)
	v_mfma_f32_32x32x16_bf16 v[66:81], v[142:145], v[94:97], v[66:81]
	v_add_u32_e32 v207, v202, v193
	s_mov_b32 m0, s6
	s_nop 0
	global_load_lds_dwordx4 v[162:163], off
	v_mfma_f32_32x32x16_bf16 v[66:81], v[130:133], v[90:93], v[66:81]
	s_add_u32 m0, s6, 0x2000
	s_nop 0
	global_load_lds_dwordx4 v[160:161], off
	v_mfma_f32_32x32x16_bf16 v[66:81], v[134:137], v[86:89], v[66:81]
	s_add_u32 m0, s6, 0x4000
	s_nop 0
	global_load_lds_dwordx4 v[158:159], off
	v_mfma_f32_32x32x16_bf16 v[66:81], v[138:141], v[82:85], v[66:81]
	s_add_u32 m0, s6, 0x6000
	v_lshl_add_u64 v[232:233], v[156:157], 0, s[0:1]
	global_load_lds_dwordx4 v[232:233], off
	v_mfma_f32_32x32x16_bf16 v[66:81], v[208:211], v[118:121], v[66:81]
	v_add_u32_e32 v208, v202, v192
	ds_read_b128 v[138:141], v208 offset:24576
	ds_read_b128 v[130:133], v208 offset:28672
	ds_read_b128 v[142:145], v207 offset:24576
	ds_read_b128 v[134:137], v207 offset:28672
	v_mfma_f32_32x32x16_bf16 v[66:81], v[212:215], v[126:129], v[66:81]
	s_add_u32 m0, s6, 0x8000
	v_lshl_add_u64 v[234:235], v[164:165], 0, s[0:1]
	global_load_lds_dwordx4 v[234:235], off
	v_mfma_f32_32x32x16_bf16 v[66:81], v[222:225], v[114:117], v[66:81]
	v_mfma_f32_32x32x16_bf16 v[66:81], v[226:229], v[122:125], v[66:81]
	s_setprio 0
	s_nop 10
	v_mul_f32_e32 v217, 0x3dd53b94, v66
	v_mul_f32_e32 v216, 0x3dd53b94, v67
	s_mov_b32 s3, 0xff800000
	v_mul_f32_e32 v215, 0x3dd53b94, v68
	v_mul_f32_e32 v214, 0x3dd53b94, v69
	v_mul_f32_e32 v210, 0x3dd53b94, v73
	v_mul_f32_e32 v73, 0x3dd53b94, v74
	v_max3_f32 v74, v217, s3, v216
	v_mul_f32_e32 v213, 0x3dd53b94, v70
	v_mul_f32_e32 v212, 0x3dd53b94, v71
	v_max3_f32 v74, v74, v215, v214
	v_mul_f32_e32 v211, 0x3dd53b94, v72
	v_max3_f32 v74, v74, v213, v212
	v_mul_f32_e32 v72, 0x3dd53b94, v75
	v_max3_f32 v74, v74, v211, v210
	v_mul_f32_e32 v71, 0x3dd53b94, v76
	v_mul_f32_e32 v70, 0x3dd53b94, v77
	v_max3_f32 v74, v74, v73, v72
	v_mul_f32_e32 v69, 0x3dd53b94, v78
	v_mul_f32_e32 v68, 0x3dd53b94, v79
	v_max3_f32 v74, v74, v71, v70
	v_mul_f32_e32 v67, 0x3dd53b94, v80
	v_mul_f32_e32 v66, 0x3dd53b94, v81
	v_max3_f32 v74, v74, v69, v68
	v_max3_f32 v74, v74, v67, v66
	ds_bpermute_b32 v75, v149, v74
	v_add_f32_e32 v209, 0x41000000, v198
	s_waitcnt lgkmcnt(0)
	v_max_f32_e32 v75, v75, v75
	v_max_f32_e32 v74, v74, v75
	v_cmp_le_f32_e32 vcc, v74, v209
	s_cmp_eq_u64 vcc, exec
	s_cbranch_scc1 .LBB0_869
	v_max_f32_e32 v74, v74, v74
	v_max_f32_e32 v75, v198, v198
	v_max_f32_e32 v75, v75, v74
	v_sub_f32_e32 v74, v198, v75
	v_exp_f32_e32 v74, v74
	v_add_f32_e32 v209, 0x41000000, v75
	v_mov_b32_e32 v198, v75
	v_mul_f32_e32 v201, v201, v74
	v_pk_mul_f32 v[64:65], v[64:65], v[74:75] op_sel_hi:[1,0]
	v_pk_mul_f32 v[62:63], v[62:63], v[74:75] op_sel_hi:[1,0]
	v_pk_mul_f32 v[60:61], v[60:61], v[74:75] op_sel_hi:[1,0]
	v_pk_mul_f32 v[58:59], v[58:59], v[74:75] op_sel_hi:[1,0]
	v_pk_mul_f32 v[56:57], v[56:57], v[74:75] op_sel_hi:[1,0]
	v_pk_mul_f32 v[54:55], v[54:55], v[74:75] op_sel_hi:[1,0]
	v_pk_mul_f32 v[52:53], v[52:53], v[74:75] op_sel_hi:[1,0]
	v_pk_mul_f32 v[50:51], v[50:51], v[74:75] op_sel_hi:[1,0]
	v_pk_mul_f32 v[48:49], v[48:49], v[74:75] op_sel_hi:[1,0]
	v_pk_mul_f32 v[46:47], v[46:47], v[74:75] op_sel_hi:[1,0]
	v_pk_mul_f32 v[44:45], v[44:45], v[74:75] op_sel_hi:[1,0]
	v_pk_mul_f32 v[42:43], v[42:43], v[74:75] op_sel_hi:[1,0]
	v_pk_mul_f32 v[40:41], v[40:41], v[74:75] op_sel_hi:[1,0]
	v_pk_mul_f32 v[38:39], v[38:39], v[74:75] op_sel_hi:[1,0]
	v_pk_mul_f32 v[36:37], v[36:37], v[74:75] op_sel_hi:[1,0]
	v_pk_mul_f32 v[34:35], v[34:35], v[74:75] op_sel_hi:[1,0]
	v_pk_mul_f32 v[32:33], v[32:33], v[74:75] op_sel_hi:[1,0]
	v_pk_mul_f32 v[30:31], v[30:31], v[74:75] op_sel_hi:[1,0]
	v_pk_mul_f32 v[28:29], v[28:29], v[74:75] op_sel_hi:[1,0]
	v_pk_mul_f32 v[26:27], v[26:27], v[74:75] op_sel_hi:[1,0]
	v_pk_mul_f32 v[24:25], v[24:25], v[74:75] op_sel_hi:[1,0]
	v_pk_mul_f32 v[22:23], v[22:23], v[74:75] op_sel_hi:[1,0]
	v_pk_mul_f32 v[20:21], v[20:21], v[74:75] op_sel_hi:[1,0]
	v_pk_mul_f32 v[18:19], v[18:19], v[74:75] op_sel_hi:[1,0]
	v_pk_mul_f32 v[16:17], v[16:17], v[74:75] op_sel_hi:[1,0]
	v_pk_mul_f32 v[14:15], v[14:15], v[74:75] op_sel_hi:[1,0]
	v_pk_mul_f32 v[12:13], v[12:13], v[74:75] op_sel_hi:[1,0]
	v_pk_mul_f32 v[10:11], v[10:11], v[74:75] op_sel_hi:[1,0]
	v_pk_mul_f32 v[8:9], v[8:9], v[74:75] op_sel_hi:[1,0]
	v_pk_mul_f32 v[6:7], v[6:7], v[74:75] op_sel_hi:[1,0]
	v_pk_mul_f32 v[4:5], v[4:5], v[74:75] op_sel_hi:[1,0]
	v_pk_mul_f32 v[2:3], v[2:3], v[74:75] op_sel_hi:[1,0]
